# P4 tail-slot conversions with the helper-workgroup split computed from the grid size (no hard-coded CU count)
# speedup vs baseline: 1.0064x; 1.0027x over previous
; #define LAS __attribute__((address_space(3)))
; __global__ void __launch_bounds__(512, 2) mk_fwd(Args args) {
;     ...
;             constexpr int NU = (M / 256) * (2 * FF / 256);
;             const int rounds = (NU + G - 1) / G, n_full = NU - (rounds - 1) * G;
;             const int nh = (n_full < G) ? G - n_full : G, hidx = (n_full < G) ? bx - n_full : bx;
;             if (hidx >= 0) {
;                 LAS float* scr = (LAS float*)(ldsl + wave * 16384);
;                 constexpr int I_1B = (FF / 64) * (DM / 32), I_IN = (DM / 64) * (NIN / 32), I_A = (1024 / 64) * (DM / 32), I_O = (DM / 64) * (DM / 32);
;                 constexpr int NLATE = I_1B + I_IN + 2 * I_A + I_O;
;                 const int first = hidx * 8 + wave, stride = nh * 8;
.LBB0_391:
	v_readlane_b32 s14, v239, 37
	s_abs_i32 s0, s14
	v_cvt_f32_u32_e32 v0, s0
	s_sub_i32 s3, 0, s0
	s_add_i32 s1, s14, 0x6bf
	s_xor_b32 s2, s1, s14
	v_rcp_iflag_f32_e32 v0, v0
	s_abs_i32 s1, s1
	s_ashr_i32 s2, s2, 31
	v_mul_f32_e32 v0, 0x4f7ffffe, v0
	v_cvt_u32_f32_e32 v0, v0
	s_nop 0
	v_readfirstlane_b32 s12, v0
	s_mul_i32 s3, s3, s12
	s_mul_hi_u32 s3, s12, s3
	s_add_i32 s12, s12, s3
	s_mul_hi_u32 s3, s1, s12
	s_mul_i32 s12, s3, s0
	s_sub_i32 s1, s1, s12
	s_add_i32 s13, s3, 1
	s_sub_i32 s12, s1, s0
	s_cmp_ge_u32 s1, s0
	s_cselect_b32 s3, s13, s3
	s_cselect_b32 s1, s12, s1
	s_add_i32 s12, s3, 1
	s_cmp_ge_u32 s1, s0
	s_cselect_b32 s0, s12, s3
	s_xor_b32 s0, s0, s2
	s_not_b32 s1, s2
	s_add_i32 s0, s1, s0
	s_mul_i32 s0, s0, s14
	s_sub_i32 s0, 0x6c0, s0
	s_cmp_lt_i32 s0, s14
	s_cselect_b32 s1, s0, 0
	s_sub_i32 s0, s61, s1
	s_cmp_lt_i32 s0, 0
	s_cbranch_scc1 .Ltail4_done
	v_readlane_b32 s2, v239, 37
	s_sub_i32 s16, s2, s1
	v_readlane_b32 s2, v239, 0
	v_readlane_b32 s3, v239, 1
	s_nop 4
	s_sub_u32 s2, s2, 0xa8
	s_subb_u32 s3, s3, 0
	s_load_dwordx2 s[78:79], s[2:3], 0x58
	s_load_dwordx4 s[80:83], s[2:3], 0x60
	s_lshl_b32 s1, s52, 14
	s_lshl_b32 s0, s0, 3
	s_add_i32 s17, s1, 0
	s_add_i32 s14, s0, s52
	s_lshl_b32 s15, s16, 3
	s_waitcnt lgkmcnt(0)
	s_cmpk_gt_i32 s14, 0x3ff
	s_cbranch_scc1 .Lt4_164
	v_lshrrev_b32_e32 v8, 5, v176
	v_and_b32_e32 v0, 31, v177
	v_lshlrev_b32_e32 v6, 2, v0
	v_mul_u32_u24_e32 v1, 0x84, v8
	v_add3_u32 v9, s17, v6, v1
	v_lshlrev_b32_e32 v1, 3, v177
	v_mov_b32_e32 v7, 0
	v_lshrrev_b32_e32 v10, 3, v176
	v_and_b32_e32 v2, 56, v1
	v_readlane_b32 s0, v239, 40
	s_waitcnt lgkmcnt(0)
	v_lshl_add_u64 v[4:5], s[78:79], 0, v[6:7]
	v_mul_u32_u24_e32 v1, 0x84, v2
	v_lshlrev_b32_e32 v6, 1, v2
	v_readlane_b32 s1, v239, 41
	v_lshlrev_b32_e32 v3, 2, v10
	s_lshl_b32 s7, s14, 5
	v_lshl_add_u64 v[6:7], s[0:1], 0, v[6:7]
	v_add3_u32 v11, s17, v1, v3
	v_or_b32_e32 v12, 8, v10
	v_or_b32_e32 v13, 16, v10
	v_or_b32_e32 v14, 24, v10
	s_lshl_b32 s6, s16, 4
	s_lshl_b32 s12, s16, 9
	s_mov_b32 s13, s7
	s_mov_b32 s18, s14
	s_branch .Lt4_154
